# hyena post loop: halo loads issued exec-masked without per-load waits (one wait per iteration)
# speedup vs baseline: 1.0215x; 1.0215x over previous
; DEV float bf2f(u16 h) { return __uint_as_float(((unsigned)h) << 16); }
; DEV float bflo(unsigned w) { return __uint_as_float(w << 16); }
; DEV float bfhi(unsigned w) { return __uint_as_float(w & 0xffff0000u); }
; DEV F8 conv8(const u16* __restrict__ row, int t, int L, float w0, float w1, float w2, float bb) {
;   const uint4 u = *(const uint4*)(row + t);
;   const float um = (t > 0) ? bf2f(row[t - 1]) : 0.f;
;   const float up = (t + 8 < L) ? bf2f(row[t + 8]) : 0.f;
;   float x[10];
;   x[0] = um;
;   x[1] = bflo(u.x); x[2] = bfhi(u.x); x[3] = bflo(u.y); x[4] = bfhi(u.y);
;   x[5] = bflo(u.z); x[6] = bfhi(u.z); x[7] = bflo(u.w); x[8] = bfhi(u.w);
;   x[9] = up;
;   F8 o;
; #pragma unroll
;   for (int j = 0; j < 8; ++j) o.v[j] = x[j] * w0 + x[j + 1] * w1 + x[j + 2] * w2 + bb;
;   return o;
; }
; template <int BG>
; DEV void hyena_item_mfma(const Params& p, int g, int item, char* smem, int half) {
;     ...
;   {
;     const float wx0_0 = cw[0 * 1536 + c], wx0_1 = cw[1 * 1536 + c], wx0_2 = cw[2 * 1536 + c], bx0 = cb[c];
;     for (int e0 = tid; e0 < BG * L / 8; e0 += 256 * 4) {
;       F8 x[4];
;       uint4 y[4];
; #pragma unroll
;       for (int u = 0; u < 4; ++u) {
;         const int e = e0 + 256 * u;
;         const int bl = e / (L / 8), t = (e % (L / 8)) * 8;
;         const int b = bgi * BG + bl;
;         x[u] = conv8(UHY + ((size_t)b * 1536 + c) * L, t, L, wx0_0, wx0_1, wx0_2, bx0);
;         y[u] = *(const uint4*)(Vl + ((t >> 6) * BG + bl) * VROW + (t & 63) * 2);
;       }
; #pragma unroll
;       for (int u = 0; u < 4; ++u) {
;         const int e = e0 + 256 * u;
;         const int bl = e / (L / 8), t = (e % (L / 8)) * 8;
;         const int b = bgi * BG + bl;
;         *(uint4*)(UHY + ((size_t)b * 1536 + 1024 + c) * L + t) =
;             make_uint4(pack2(bflo(y[u].x) * x[u].v[0], bfhi(y[u].x) * x[u].v[1]), pack2(bflo(y[u].y) * x[u].v[2], bfhi(y[u].y) * x[u].v[3]),
;                        pack2(bflo(y[u].z) * x[u].v[4], bfhi(y[u].z) * x[u].v[5]), pack2(bflo(y[u].w) * x[u].v[6], bfhi(y[u].w) * x[u].v[7]));
;       }
.LBB0_755:
	s_or_b64 exec, exec, s[8:9]
	s_waitcnt vmcnt(0)
	v_lshlrev_b32_e32 v49, 16, v76
	v_lshlrev_b32_e32 v51, 16, v77
	v_lshlrev_b32_e32 v52, 16, v78
	v_lshlrev_b32_e32 v53, 16, v79
	v_lshlrev_b32_e32 v54, 16, v80
	v_lshlrev_b32_e32 v31, 16, v81
	v_lshlrev_b32_e32 v33, 16, v82
	s_waitcnt vmcnt(1)
	v_lshlrev_b32_e32 v35, 16, v24
	v_and_b32_e32 v24, 0xffff0000, v24
	v_mul_f32_e32 v56, v39, v24
	v_lshlrev_b32_e32 v36, 16, v25
	v_fmac_f32_e32 v56, v38, v35
	v_mul_f32_e32 v53, v38, v53
	v_fmac_f32_e32 v56, v40, v36
	v_fmac_f32_e32 v53, v39, v35
	v_add_f32_e32 v35, v41, v56
	v_mul_f32_e32 v56, v39, v36
	v_and_b32_e32 v25, 0xffff0000, v25
	v_fmac_f32_e32 v56, v38, v24
	v_fmac_f32_e32 v56, v40, v25
	v_fmac_f32_e32 v53, v40, v24
	v_add_f32_e32 v24, v41, v56
	v_mul_f32_e32 v56, v39, v25
	v_lshlrev_b32_e32 v37, 16, v26
	v_fmac_f32_e32 v56, v38, v36
	v_fmac_f32_e32 v56, v40, v37
	v_add_f32_e32 v36, v41, v56
	v_mul_f32_e32 v56, v39, v37
	v_and_b32_e32 v26, 0xffff0000, v26
	v_fmac_f32_e32 v56, v38, v25
	v_fmac_f32_e32 v56, v40, v26
	v_add_f32_e32 v25, v41, v56
	v_mul_f32_e32 v56, v39, v26
	v_lshlrev_b32_e32 v55, 16, v27
	v_fmac_f32_e32 v56, v38, v37
	v_fmac_f32_e32 v56, v40, v55
	v_add_f32_e32 v37, v41, v56
	v_mul_f32_e32 v56, v39, v55
	v_and_b32_e32 v27, 0xffff0000, v27
	v_fmac_f32_e32 v56, v38, v26
	v_fmac_f32_e32 v56, v40, v27
	v_mul_f32_e32 v27, v39, v27
	v_fmac_f32_e32 v27, v38, v55
	v_fmac_f32_e32 v27, v40, v54
	v_lshlrev_b32_e32 v54, 16, v16
	v_and_b32_e32 v16, 0xffff0000, v16
	v_mul_f32_e32 v58, v39, v16
	v_lshlrev_b32_e32 v55, 16, v17
	v_fmac_f32_e32 v58, v38, v54
	v_mul_f32_e32 v51, v38, v51
	v_fmac_f32_e32 v58, v40, v55
	v_and_b32_e32 v17, 0xffff0000, v17
	v_fmac_f32_e32 v51, v39, v54
	v_add_f32_e32 v54, v41, v58
	v_mul_f32_e32 v58, v39, v55
	v_fmac_f32_e32 v51, v40, v16
	v_fmac_f32_e32 v58, v38, v16
	v_mul_f32_e32 v16, v39, v17
	v_add_f32_e32 v26, v41, v56
	v_lshlrev_b32_e32 v56, 16, v18
	v_fmac_f32_e32 v16, v38, v55
	v_fmac_f32_e32 v16, v40, v56
	v_add_f32_e32 v55, v41, v16
	v_mul_f32_e32 v16, v39, v56
	v_and_b32_e32 v18, 0xffff0000, v18
	v_fmac_f32_e32 v16, v38, v17
	v_fmac_f32_e32 v16, v40, v18
	v_add_f32_e32 v59, v41, v16
	v_mul_f32_e32 v16, v39, v18
	v_lshlrev_b32_e32 v57, 16, v19
	v_fmac_f32_e32 v16, v38, v56
	v_fmac_f32_e32 v16, v40, v57
	v_add_f32_e32 v56, v41, v16
	v_mul_f32_e32 v16, v39, v57
	v_and_b32_e32 v19, 0xffff0000, v19
	v_fmac_f32_e32 v16, v38, v18
	v_fmac_f32_e32 v16, v40, v19
	v_fmac_f32_e32 v58, v40, v17
	v_add_f32_e32 v60, v41, v16
	v_mul_f32_e32 v16, v39, v19
	v_lshlrev_b32_e32 v17, 16, v12
	v_and_b32_e32 v12, 0xffff0000, v12
	v_fmac_f32_e32 v16, v38, v57
	v_mul_f32_e32 v57, v39, v12
	v_lshlrev_b32_e32 v18, 16, v13
	v_fmac_f32_e32 v57, v38, v17
	v_mul_f32_e32 v49, v38, v49
	v_fmac_f32_e32 v57, v40, v18
	v_and_b32_e32 v13, 0xffff0000, v13
	v_fmac_f32_e32 v49, v39, v17
	v_add_f32_e32 v17, v41, v57
	v_mul_f32_e32 v57, v39, v18
	v_fmac_f32_e32 v49, v40, v12
	v_fmac_f32_e32 v57, v38, v12
	v_mul_f32_e32 v12, v39, v13
	v_lshlrev_b32_e32 v19, 16, v14
	v_fmac_f32_e32 v12, v38, v18
	v_fmac_f32_e32 v12, v40, v19
	v_add_f32_e32 v18, v41, v12
	v_mul_f32_e32 v12, v39, v19
	v_and_b32_e32 v14, 0xffff0000, v14
	v_fmac_f32_e32 v12, v38, v13
	v_fmac_f32_e32 v12, v40, v14
	v_fmac_f32_e32 v16, v40, v52
	v_add_f32_e32 v61, v41, v12
	v_mul_f32_e32 v12, v39, v14
	v_add_f32_e32 v52, v41, v16
	v_lshlrev_b32_e32 v16, 16, v50
	v_lshlrev_b32_e32 v50, 16, v15
	v_fmac_f32_e32 v12, v38, v19
	v_fmac_f32_e32 v12, v40, v50
	v_add_f32_e32 v19, v41, v12
	v_mul_f32_e32 v12, v39, v50
	v_and_b32_e32 v15, 0xffff0000, v15
	v_fmac_f32_e32 v12, v38, v14
	v_fmac_f32_e32 v12, v40, v15
	v_add_f32_e32 v62, v41, v12
	v_mul_f32_e32 v12, v39, v15
	v_fmac_f32_e32 v12, v38, v50
	v_fmac_f32_e32 v12, v40, v16
	v_add_f32_e32 v16, v41, v12
	s_waitcnt vmcnt(0)
	v_lshlrev_b32_e32 v12, 16, v20
	v_mul_f32_e32 v31, v38, v31
	v_fmac_f32_e32 v57, v40, v13
	v_and_b32_e32 v13, 0xffff0000, v20
	v_fmac_f32_e32 v31, v39, v12
	v_fmac_f32_e32 v31, v40, v13
	v_lshlrev_b32_e32 v14, 16, v21
	v_add_f32_e32 v50, v41, v31
	v_mul_f32_e32 v31, v39, v13
	v_fmac_f32_e32 v31, v38, v12
	v_mul_f32_e32 v12, v39, v14
	v_and_b32_e32 v15, 0xffff0000, v21
	v_fmac_f32_e32 v12, v38, v13
	v_fmac_f32_e32 v12, v40, v15
	v_add_f32_e32 v64, v41, v12
	v_mul_f32_e32 v12, v39, v15
	v_lshlrev_b32_e32 v20, 16, v22
	v_fmac_f32_e32 v12, v38, v14
	v_fmac_f32_e32 v12, v40, v20
	v_add_f32_e32 v65, v41, v12
	v_mul_f32_e32 v12, v39, v20
	v_and_b32_e32 v21, 0xffff0000, v22
	v_fmac_f32_e32 v12, v38, v15
	v_fmac_f32_e32 v12, v40, v21
	v_add_f32_e32 v66, v41, v12
	v_mul_f32_e32 v12, v39, v21
	v_lshlrev_b32_e32 v22, 16, v23
	v_fmac_f32_e32 v12, v38, v20
	v_fmac_f32_e32 v12, v40, v22
	v_add_f32_e32 v20, v41, v12
	v_mul_f32_e32 v12, v39, v22
	v_and_b32_e32 v23, 0xffff0000, v23
	v_fmac_f32_e32 v12, v38, v21
	v_fmac_f32_e32 v12, v40, v23
	v_add_f32_e32 v21, v41, v12
	v_mul_f32_e32 v12, v39, v23
	s_waitcnt lgkmcnt(2)
	v_lshlrev_b32_e32 v23, 16, v0
	v_and_b32_e32 v0, 0xffff0000, v0
	v_add_f32_e32 v57, v41, v57
	v_mul_f32_e32 v0, v17, v0
	v_lshlrev_b32_e32 v17, 16, v1
	v_and_b32_e32 v1, 0xffff0000, v1
	v_mul_f32_e32 v17, v57, v17
	v_mul_f32_e32 v1, v18, v1
	s_nop 0
	v_cvt_pk_bf16_f32 v1, v17, v1
	v_lshlrev_b32_e32 v17, 16, v2
	v_and_b32_e32 v2, 0xffff0000, v2
	v_mul_f32_e32 v17, v61, v17
	v_mul_f32_e32 v2, v19, v2
	s_nop 0
	v_cvt_pk_bf16_f32 v2, v17, v2
	v_lshlrev_b32_e32 v17, 16, v3
	v_and_b32_e32 v3, 0xffff0000, v3
	v_mul_f32_e32 v17, v62, v17
	v_mul_f32_e32 v3, v16, v3
	v_add_u32_e32 v164, 0x400, v164
	s_nop 0
	v_cvt_pk_bf16_f32 v3, v17, v3
	v_lshl_add_u64 v[16:17], v[164:165], 0, s[18:19]
	v_add_f32_e32 v49, v41, v49
	v_lshlrev_b64 v[16:17], 14, v[16:17]
	v_mul_f32_e32 v23, v49, v23
	s_nop 0
	v_cvt_pk_bf16_f32 v0, v23, v0
	v_lshl_add_u64 v[18:19], v[28:29], 0, v[16:17]
	v_add_f32_e32 v51, v41, v51
	global_store_dwordx4 v[18:19], v[0:3], off
	v_add_f32_e32 v58, v41, v58
	v_fmac_f32_e32 v31, v40, v14
	s_waitcnt lgkmcnt(1)
; DEV float bf2f(u16 h) { return __uint_as_float(((unsigned)h) << 16); }
; DEV float bflo(unsigned w) { return __uint_as_float(w << 16); }
; DEV float bfhi(unsigned w) { return __uint_as_float(w & 0xffff0000u); }
; DEV F8 conv8(const u16* __restrict__ row, int t, int L, float w0, float w1, float w2, float bb) {
;   const uint4 u = *(const uint4*)(row + t);
;   const float um = (t > 0) ? bf2f(row[t - 1]) : 0.f;
;   const float up = (t + 8 < L) ? bf2f(row[t + 8]) : 0.f;
;   float x[10];
;   x[0] = um;
;   x[1] = bflo(u.x); x[2] = bfhi(u.x); x[3] = bflo(u.y); x[4] = bfhi(u.y);
;   x[5] = bflo(u.z); x[6] = bfhi(u.z); x[7] = bflo(u.w); x[8] = bfhi(u.w);
;   x[9] = up;
;   F8 o;
; #pragma unroll
;   for (int j = 0; j < 8; ++j) o.v[j] = x[j] * w0 + x[j + 1] * w1 + x[j + 2] * w2 + bb;
;   return o;
; }
; template <int BG>
; DEV void hyena_item_mfma(const Params& p, int g, int item, char* smem, int half) {
;     ...
;     for (int e0 = tid; e0 < BG * L / 8; e0 += 256 * 4) {
;       F8 x[4];
;       uint4 y[4];
; #pragma unroll
;       for (int u = 0; u < 4; ++u) {
;         const int e = e0 + 256 * u;
;         const int bl = e / (L / 8), t = (e % (L / 8)) * 8;
;         const int b = bgi * BG + bl;
;         x[u] = conv8(UHY + ((size_t)b * 1536 + c) * L, t, L, wx0_0, wx0_1, wx0_2, bx0);
;         y[u] = *(const uint4*)(Vl + ((t >> 6) * BG + bl) * VROW + (t & 63) * 2);
;       }
; #pragma unroll
;       for (int u = 0; u < 4; ++u) {
;         const int e = e0 + 256 * u;
;         const int bl = e / (L / 8), t = (e % (L / 8)) * 8;
;         const int b = bgi * BG + bl;
;         *(uint4*)(UHY + ((size_t)b * 1536 + 1024 + c) * L + t) =
;             make_uint4(pack2(bflo(y[u].x) * x[u].v[0], bfhi(y[u].x) * x[u].v[1]), pack2(bflo(y[u].y) * x[u].v[2], bfhi(y[u].y) * x[u].v[3]),
;                        pack2(bflo(y[u].z) * x[u].v[4], bfhi(y[u].z) * x[u].v[5]), pack2(bflo(y[u].w) * x[u].v[6], bfhi(y[u].w) * x[u].v[7]));
;       }
	v_lshlrev_b32_e32 v0, 16, v4
	v_and_b32_e32 v1, 0xffff0000, v4
	v_mul_f32_e32 v0, v51, v0
	v_mul_f32_e32 v1, v54, v1
	s_nop 0
	v_cvt_pk_bf16_f32 v0, v0, v1
	v_lshlrev_b32_e32 v1, 16, v5
	v_and_b32_e32 v2, 0xffff0000, v5
	v_mul_f32_e32 v1, v58, v1
	v_mul_f32_e32 v2, v55, v2
	s_nop 0
	v_cvt_pk_bf16_f32 v1, v1, v2
	v_lshlrev_b32_e32 v2, 16, v6
	v_and_b32_e32 v3, 0xffff0000, v6
	v_mul_f32_e32 v2, v59, v2
	v_mul_f32_e32 v3, v56, v3
	s_nop 0
	v_cvt_pk_bf16_f32 v2, v2, v3
	v_lshlrev_b32_e32 v3, 16, v7
	v_and_b32_e32 v4, 0xffff0000, v7
	v_mul_f32_e32 v3, v60, v3
	v_mul_f32_e32 v4, v52, v4
	v_add_f32_e32 v63, v41, v31
	s_nop 0
	v_cvt_pk_bf16_f32 v3, v3, v4
	v_lshl_add_u64 v[4:5], s[74:75], 0, v[16:17]
	v_mov_b32_e32 v31, v165
	v_lshl_add_u64 v[6:7], v[4:5], 0, v[30:31]
	v_add_f32_e32 v53, v41, v53
	v_fmac_f32_e32 v12, v38, v22
	global_store_dwordx4 v[6:7], v[0:3], off
	v_fmac_f32_e32 v12, v40, v33
	v_add_f32_e32 v22, v41, v12
	s_waitcnt lgkmcnt(0)
	v_lshlrev_b32_e32 v0, 16, v8
	v_and_b32_e32 v1, 0xffff0000, v8
	v_mul_f32_e32 v0, v53, v0
	v_mul_f32_e32 v1, v35, v1
	v_add_u32_e32 v12, s10, v44
	s_nop 0
	v_cvt_pk_bf16_f32 v0, v0, v1
	v_lshlrev_b32_e32 v1, 16, v9
	v_and_b32_e32 v2, 0xffff0000, v9
	v_mad_u32_u24 v12, v12, s60, v42
	v_mul_f32_e32 v1, v24, v1
	v_mul_f32_e32 v2, v36, v2
	ds_read_b128 v[12:15], v12
	s_nop 0
	v_cvt_pk_bf16_f32 v1, v1, v2
	v_lshlrev_b32_e32 v2, 16, v10
	v_and_b32_e32 v3, 0xffff0000, v10
	v_mul_f32_e32 v2, v25, v2
	v_mul_f32_e32 v3, v37, v3
	v_add_f32_e32 v27, v41, v27
	s_nop 0
	v_cvt_pk_bf16_f32 v2, v2, v3
	v_lshlrev_b32_e32 v3, 16, v11
	v_and_b32_e32 v6, 0xffff0000, v11
	v_mul_f32_e32 v3, v26, v3
	v_mul_f32_e32 v6, v27, v6
	v_mov_b32_e32 v33, v165
	s_nop 0
	v_cvt_pk_bf16_f32 v3, v3, v6
	v_lshl_add_u64 v[6:7], v[4:5], 0, v[32:33]
	global_store_dwordx4 v[6:7], v[0:3], off
	v_add_co_u32_e32 v144, vcc, 0x400, v144
	s_waitcnt lgkmcnt(0)
	v_lshlrev_b32_e32 v0, 16, v12
	v_and_b32_e32 v1, 0xffff0000, v12
	v_mul_f32_e32 v0, v50, v0
	v_mul_f32_e32 v1, v63, v1
	s_nop 0
	v_cvt_pk_bf16_f32 v0, v0, v1
	v_lshlrev_b32_e32 v1, 16, v13
	v_and_b32_e32 v2, 0xffff0000, v13
	v_mul_f32_e32 v1, v64, v1
	v_mul_f32_e32 v2, v65, v2
	s_nop 0
	v_cvt_pk_bf16_f32 v1, v1, v2
	v_lshlrev_b32_e32 v2, 16, v14
	v_and_b32_e32 v3, 0xffff0000, v14
	v_mul_f32_e32 v2, v66, v2
	v_mul_f32_e32 v3, v20, v3
	s_xor_b64 s[8:9], vcc, -1
	s_add_i32 s10, s10, 1
	s_nop 0
	v_cvt_pk_bf16_f32 v2, v2, v3
	v_lshlrev_b32_e32 v3, 16, v15
	v_mov_b32_e32 v35, v165
	s_and_b64 s[8:9], exec, s[8:9]
	v_mul_f32_e32 v3, v21, v3
	v_and_b32_e32 v6, 0xffff0000, v15
	v_lshl_add_u64 v[4:5], v[4:5], 0, v[34:35]
	v_add_u32_e32 v43, 0x2000, v43
	s_or_b64 s[4:5], s[8:9], s[4:5]
	v_add_u32_e32 v145, 0x4000, v145
	v_mul_f32_e32 v6, v22, v6
	s_nop 0
	v_cvt_pk_bf16_f32 v3, v3, v6
	global_store_dwordx4 v[4:5], v[0:3], off
	s_andn2_b64 exec, exec, s[4:5]
	s_cbranch_execz .LBB0_770
.LBB0_756:
	v_add_u32_e32 v0, s10, v45
	v_mul_u32_u24_e32 v164, 0x600, v0
	v_lshl_add_u64 v[0:1], v[164:165], 0, s[18:19]
	v_lshlrev_b64 v[4:5], 14, v[0:1]
	v_lshl_add_u64 v[0:1], v[28:29], 0, v[4:5]
	global_load_dwordx4 v[12:15], v[0:1], off
	v_mov_b32_e32 v51, 0
	v_mov_b32_e32 v49, 0
	v_mov_b32_e32 v76, 0
	s_and_saveexec_b64 s[8:9], s[0:1]
	global_load_ushort v76, v[0:1], off offset:-2
.LBB0_758:
	s_or_b64 exec, exec, s[8:9]
	v_add_u32_e32 v6, 0xfffff000, v43
	v_and_b32_e32 v6, 0x1ff8, v6
	v_lshl_add_u64 v[4:5], s[74:75], 0, v[4:5]
	v_lshlrev_b32_e32 v30, 1, v6
	v_mov_b32_e32 v31, v165
	v_lshl_add_u64 v[4:5], v[4:5], 0, v[30:31]
	global_load_ushort v50, v[0:1], off offset:16
	global_load_dwordx4 v[16:19], v[4:5], off
	v_add_u32_e32 v0, s10, v48
	v_mul_u32_u24_e32 v0, 0x90, v0
	v_and_b32_e32 v1, 0x70, v145
	v_add3_u32 v0, s27, v0, v1
	ds_read_b128 v[0:3], v0
	v_cmp_ne_u32_e32 vcc, 0, v6
	v_mov_b32_e32 v77, 0
	s_and_saveexec_b64 s[8:9], vcc
	global_load_ushort v77, v[4:5], off offset:-2
.LBB0_760:
	s_or_b64 exec, exec, s[8:9]
	s_movk_i32 s8, 0x1ff8
	v_cmp_ne_u32_e32 vcc, s8, v6
	v_mov_b32_e32 v53, 0
	v_mov_b32_e32 v52, 0
	v_mov_b32_e32 v78, 0
	s_and_saveexec_b64 s[8:9], vcc
	global_load_ushort v78, v[4:5], off offset:16
.LBB0_762:
	s_or_b64 exec, exec, s[8:9]
	v_add_u32_e32 v8, 0xfffff800, v43
	v_and_b32_e32 v10, 0x1ff8, v8
	v_lshl_add_u64 v[8:9], v[164:165], 0, s[18:19]
	v_lshlrev_b64 v[8:9], 14, v[8:9]
	v_lshl_add_u64 v[8:9], s[74:75], 0, v[8:9]
	v_lshlrev_b32_e32 v32, 1, v10
	v_mov_b32_e32 v33, v165
	v_lshl_add_u64 v[8:9], v[8:9], 0, v[32:33]
	global_load_dwordx4 v[24:27], v[8:9], off
	v_add_u32_e32 v4, s10, v47
	v_mad_u32_u24 v4, v4, s60, v42
	ds_read_b128 v[4:7], v4
	v_cmp_ne_u32_e32 vcc, 0, v10
	v_mov_b32_e32 v79, 0
	s_and_saveexec_b64 s[8:9], vcc
	global_load_ushort v79, v[8:9], off offset:-2
.LBB0_764:
	s_or_b64 exec, exec, s[8:9]
	s_movk_i32 s8, 0x1ff8
	v_cmp_ne_u32_e32 vcc, s8, v10
	v_mov_b32_e32 v31, 0
	v_mov_b32_e32 v54, 0
	v_mov_b32_e32 v80, 0
	s_and_saveexec_b64 s[8:9], vcc
	global_load_ushort v80, v[8:9], off offset:16
.LBB0_766:
	s_or_b64 exec, exec, s[8:9]
	v_lshl_add_u64 v[20:21], v[164:165], 0, s[18:19]
	v_and_b32_e32 v33, 0x1ff8, v43
	v_lshlrev_b64 v[20:21], 14, v[20:21]
	v_lshl_add_u64 v[20:21], s[74:75], 0, v[20:21]
	v_lshlrev_b32_e32 v34, 1, v33
	v_mov_b32_e32 v35, v165
	v_lshl_add_u64 v[36:37], v[20:21], 0, v[34:35]
	global_load_dwordx4 v[20:23], v[36:37], off
	v_add_u32_e32 v8, s10, v46
	v_mad_u32_u24 v8, v8, s60, v42
	ds_read_b128 v[8:11], v8
	v_cmp_ne_u32_e32 vcc, 0, v33
	v_mov_b32_e32 v81, 0
	s_and_saveexec_b64 s[8:9], vcc
	global_load_ushort v81, v[36:37], off offset:-2
.LBB0_768:
	s_or_b64 exec, exec, s[8:9]
	s_movk_i32 s8, 0x1ff8
	v_cmp_ne_u32_e32 vcc, s8, v33
	v_mov_b32_e32 v33, 0
	v_mov_b32_e32 v82, 0
	s_and_saveexec_b64 s[8:9], vcc
	global_load_ushort v82, v[36:37], off offset:16
	s_or_b64 exec, exec, s[8:9]
	s_branch .LBB0_755

; DEV float bf2f(u16 h) { return __uint_as_float(((unsigned)h) << 16); }
; DEV float bflo(unsigned w) { return __uint_as_float(w << 16); }
; DEV float bfhi(unsigned w) { return __uint_as_float(w & 0xffff0000u); }
; DEV F8 conv8(const u16* __restrict__ row, int t, int L, float w0, float w1, float w2, float bb) {
;   const uint4 u = *(const uint4*)(row + t);
;   const float um = (t > 0) ? bf2f(row[t - 1]) : 0.f;
;   const float up = (t + 8 < L) ? bf2f(row[t + 8]) : 0.f;
;   float x[10];
;   x[0] = um;
;   x[1] = bflo(u.x); x[2] = bfhi(u.x); x[3] = bflo(u.y); x[4] = bfhi(u.y);
;   x[5] = bflo(u.z); x[6] = bfhi(u.z); x[7] = bflo(u.w); x[8] = bfhi(u.w);
;   x[9] = up;
;   F8 o;
; #pragma unroll
;   for (int j = 0; j < 8; ++j) o.v[j] = x[j] * w0 + x[j + 1] * w1 + x[j + 2] * w2 + bb;
;   return o;
; }
; template <int BG>
; DEV void hyena_item_mfma(const Params& p, int g, int item, char* smem, int half) {
;     ...
;   {
;     const float wx0_0 = cw[0 * 1536 + c], wx0_1 = cw[1 * 1536 + c], wx0_2 = cw[2 * 1536 + c], bx0 = cb[c];
;     for (int e0 = tid; e0 < BG * L / 8; e0 += 256 * 4) {
;       F8 x[4];
;       uint4 y[4];
; #pragma unroll
;       for (int u = 0; u < 4; ++u) {
;         const int e = e0 + 256 * u;
;         const int bl = e / (L / 8), t = (e % (L / 8)) * 8;
;         const int b = bgi * BG + bl;
;         x[u] = conv8(UHY + ((size_t)b * 1536 + c) * L, t, L, wx0_0, wx0_1, wx0_2, bx0);
;         y[u] = *(const uint4*)(Vl + ((t >> 6) * BG + bl) * VROW + (t & 63) * 2);
;       }
; #pragma unroll
;       for (int u = 0; u < 4; ++u) {
;         const int e = e0 + 256 * u;
;         const int bl = e / (L / 8), t = (e % (L / 8)) * 8;
;         const int b = bgi * BG + bl;
;         *(uint4*)(UHY + ((size_t)b * 1536 + 1024 + c) * L + t) =
;             make_uint4(pack2(bflo(y[u].x) * x[u].v[0], bfhi(y[u].x) * x[u].v[1]), pack2(bflo(y[u].y) * x[u].v[2], bfhi(y[u].y) * x[u].v[3]),
;                        pack2(bflo(y[u].z) * x[u].v[4], bfhi(y[u].z) * x[u].v[5]), pack2(bflo(y[u].w) * x[u].v[6], bfhi(y[u].w) * x[u].v[7]));
;       }
.LBB0_795:
	s_or_b64 exec, exec, s[8:9]
	s_waitcnt vmcnt(0)
	v_lshlrev_b32_e32 v51, 16, v76
	v_lshlrev_b32_e32 v53, 16, v77
	v_lshlrev_b32_e32 v54, 16, v78
	v_lshlrev_b32_e32 v55, 16, v79
	v_lshlrev_b32_e32 v33, 16, v80
	s_waitcnt vmcnt(3)
	v_lshlrev_b32_e32 v37, 16, v24
	v_and_b32_e32 v24, 0xffff0000, v24
	v_mul_f32_e32 v59, v39, v24
	s_waitcnt vmcnt(2)
	v_lshlrev_b32_e32 v36, 16, v56
	v_lshlrev_b32_e32 v56, 16, v25
	v_fmac_f32_e32 v59, v38, v37
	v_mul_f32_e32 v55, v38, v55
	v_fmac_f32_e32 v59, v40, v56
	v_fmac_f32_e32 v55, v39, v37
	v_add_f32_e32 v37, v41, v59
	v_mul_f32_e32 v59, v39, v56
	v_and_b32_e32 v25, 0xffff0000, v25
	v_fmac_f32_e32 v59, v38, v24
	v_fmac_f32_e32 v59, v40, v25
	v_fmac_f32_e32 v55, v40, v24
	v_add_f32_e32 v24, v41, v59
	v_mul_f32_e32 v59, v39, v25
	v_lshlrev_b32_e32 v57, 16, v26
	v_fmac_f32_e32 v59, v38, v56
	v_fmac_f32_e32 v59, v40, v57
	v_add_f32_e32 v56, v41, v59
	v_mul_f32_e32 v59, v39, v57
	v_and_b32_e32 v26, 0xffff0000, v26
	v_fmac_f32_e32 v59, v38, v25
	v_fmac_f32_e32 v59, v40, v26
	v_add_f32_e32 v25, v41, v59
	v_mul_f32_e32 v59, v39, v26
	v_lshlrev_b32_e32 v58, 16, v27
	v_fmac_f32_e32 v59, v38, v57
	v_fmac_f32_e32 v59, v40, v58
	v_add_f32_e32 v57, v41, v59
	v_mul_f32_e32 v59, v39, v58
	v_and_b32_e32 v27, 0xffff0000, v27
	v_fmac_f32_e32 v59, v38, v26
	v_fmac_f32_e32 v59, v40, v27
	v_mul_f32_e32 v27, v39, v27
	v_fmac_f32_e32 v27, v38, v58
	v_fmac_f32_e32 v27, v40, v36
	v_lshlrev_b32_e32 v36, 16, v20
	v_and_b32_e32 v20, 0xffff0000, v20
	v_mul_f32_e32 v61, v39, v20
	v_lshlrev_b32_e32 v58, 16, v21
	v_fmac_f32_e32 v61, v38, v36
	v_mul_f32_e32 v53, v38, v53
	v_fmac_f32_e32 v61, v40, v58
	v_fmac_f32_e32 v53, v39, v36
	v_add_f32_e32 v36, v41, v61
	v_mul_f32_e32 v61, v39, v58
	v_and_b32_e32 v21, 0xffff0000, v21
	v_fmac_f32_e32 v61, v38, v20
	v_fmac_f32_e32 v61, v40, v21
	v_fmac_f32_e32 v53, v40, v20
	v_add_f32_e32 v20, v41, v61
	v_mul_f32_e32 v61, v39, v21
	v_add_f32_e32 v26, v41, v59
	v_lshlrev_b32_e32 v59, 16, v22
	v_fmac_f32_e32 v61, v38, v58
	v_fmac_f32_e32 v61, v40, v59
	v_add_f32_e32 v58, v41, v61
	v_mul_f32_e32 v61, v39, v59
	v_and_b32_e32 v22, 0xffff0000, v22
	v_fmac_f32_e32 v61, v38, v21
	v_fmac_f32_e32 v61, v40, v22
	v_add_f32_e32 v21, v41, v61
	v_mul_f32_e32 v61, v39, v22
	v_lshlrev_b32_e32 v60, 16, v23
	v_fmac_f32_e32 v61, v38, v59
	v_fmac_f32_e32 v61, v40, v60
	v_add_f32_e32 v59, v41, v61
	v_mul_f32_e32 v61, v39, v60
	v_and_b32_e32 v23, 0xffff0000, v23
	v_fmac_f32_e32 v61, v38, v22
	v_fmac_f32_e32 v61, v40, v23
	v_mul_f32_e32 v23, v39, v23
	v_fmac_f32_e32 v23, v38, v60
	v_fmac_f32_e32 v23, v40, v54
	v_lshlrev_b32_e32 v54, 16, v12
	v_and_b32_e32 v12, 0xffff0000, v12
	v_mul_f32_e32 v63, v39, v12
	v_lshlrev_b32_e32 v60, 16, v13
	v_fmac_f32_e32 v63, v38, v54
	v_mul_f32_e32 v51, v38, v51
	v_fmac_f32_e32 v63, v40, v60
	v_and_b32_e32 v13, 0xffff0000, v13
	v_fmac_f32_e32 v51, v39, v54
	v_add_f32_e32 v54, v41, v63
	v_mul_f32_e32 v63, v39, v60
	v_fmac_f32_e32 v51, v40, v12
	v_fmac_f32_e32 v63, v38, v12
	v_mul_f32_e32 v12, v39, v13
	v_add_f32_e32 v22, v41, v61
	v_lshlrev_b32_e32 v61, 16, v14
	v_fmac_f32_e32 v12, v38, v60
	v_fmac_f32_e32 v12, v40, v61
	v_add_f32_e32 v60, v41, v12
	v_mul_f32_e32 v12, v39, v61
	v_and_b32_e32 v14, 0xffff0000, v14
	v_fmac_f32_e32 v12, v38, v13
	v_fmac_f32_e32 v12, v40, v14
	v_add_f32_e32 v64, v41, v12
	v_mul_f32_e32 v12, v39, v14
	v_lshlrev_b32_e32 v62, 16, v15
	v_fmac_f32_e32 v12, v38, v61
	v_fmac_f32_e32 v12, v40, v62
	v_add_f32_e32 v61, v41, v12
	v_mul_f32_e32 v12, v39, v62
	v_and_b32_e32 v15, 0xffff0000, v15
	v_fmac_f32_e32 v12, v38, v14
	v_fmac_f32_e32 v12, v40, v15
	v_add_f32_e32 v65, v41, v12
	v_mul_f32_e32 v12, v39, v15
	v_lshlrev_b32_e32 v52, 16, v52
	v_fmac_f32_e32 v12, v38, v62
	s_waitcnt vmcnt(0)
	v_lshlrev_b32_e32 v35, 16, v35
	v_fmac_f32_e32 v63, v40, v13
	v_fmac_f32_e32 v12, v40, v52
	v_and_b32_e32 v13, 0xffff0000, v16
	v_add_f32_e32 v52, v41, v12
	v_lshlrev_b32_e32 v12, 16, v16
	v_lshlrev_b32_e32 v14, 16, v17
	v_mul_f32_e32 v35, v38, v35
	v_mul_f32_e32 v62, v39, v13
	v_fmac_f32_e32 v35, v39, v12
	v_fmac_f32_e32 v62, v38, v12
	v_mul_f32_e32 v12, v39, v14
	v_and_b32_e32 v15, 0xffff0000, v17
	v_fmac_f32_e32 v12, v38, v13
	v_fmac_f32_e32 v12, v40, v15
	v_add_f32_e32 v66, v41, v12
	v_mul_f32_e32 v12, v39, v15
	v_lshlrev_b32_e32 v16, 16, v18
	v_fmac_f32_e32 v12, v38, v14
	v_fmac_f32_e32 v12, v40, v16
	v_add_f32_e32 v67, v41, v12
	v_mul_f32_e32 v12, v39, v16
	v_and_b32_e32 v17, 0xffff0000, v18
	v_fmac_f32_e32 v12, v38, v15
	v_fmac_f32_e32 v12, v40, v17
	v_add_f32_e32 v68, v41, v12
	v_mul_f32_e32 v12, v39, v17
	v_add_f32_e32 v51, v41, v51
	v_fmac_f32_e32 v12, v38, v16
	s_waitcnt lgkmcnt(2)
	v_lshlrev_b32_e32 v16, 16, v0
	v_and_b32_e32 v0, 0xffff0000, v0
	v_mul_f32_e32 v16, v51, v16
	v_mul_f32_e32 v0, v54, v0
	v_add_f32_e32 v63, v41, v63
	s_nop 0
	v_cvt_pk_bf16_f32 v0, v16, v0
	v_lshlrev_b32_e32 v16, 16, v1
	v_and_b32_e32 v1, 0xffff0000, v1
	v_mul_f32_e32 v16, v63, v16
	v_mul_f32_e32 v1, v60, v1
	v_lshlrev_b32_e32 v18, 16, v19
	s_nop 0
	v_cvt_pk_bf16_f32 v1, v16, v1
	v_lshlrev_b32_e32 v16, 16, v2
	v_and_b32_e32 v2, 0xffff0000, v2
	v_fmac_f32_e32 v12, v40, v18
	v_mul_f32_e32 v16, v64, v16
	v_mul_f32_e32 v2, v61, v2
	v_add_f32_e32 v69, v41, v12
	v_mul_f32_e32 v12, v39, v18
	s_nop 0
	v_cvt_pk_bf16_f32 v2, v16, v2
	v_lshlrev_b32_e32 v16, 16, v3
	v_and_b32_e32 v3, 0xffff0000, v3
	v_and_b32_e32 v19, 0xffff0000, v19
	v_fmac_f32_e32 v12, v38, v17
	v_mul_f32_e32 v16, v65, v16
	v_mul_f32_e32 v3, v52, v3
	v_add_u32_e32 v164, 0x400, v164
	v_fmac_f32_e32 v12, v40, v19
	s_nop 0
	v_cvt_pk_bf16_f32 v3, v16, v3
	v_lshl_add_u64 v[16:17], v[164:165], 0, s[18:19]
	v_add_f32_e32 v70, v41, v12
	v_mul_f32_e32 v12, v39, v19
	v_lshlrev_b64 v[16:17], 13, v[16:17]
	v_fmac_f32_e32 v12, v38, v18
	v_lshl_add_u64 v[18:19], v[28:29], 0, v[16:17]
	v_add_f32_e32 v53, v41, v53
	global_store_dwordx4 v[18:19], v[0:3], off
	v_add_f32_e32 v23, v41, v23
	v_fmac_f32_e32 v12, v40, v33
	s_waitcnt lgkmcnt(1)
; DEV float bf2f(u16 h) { return __uint_as_float(((unsigned)h) << 16); }
; DEV float bflo(unsigned w) { return __uint_as_float(w << 16); }
; DEV float bfhi(unsigned w) { return __uint_as_float(w & 0xffff0000u); }
; DEV F8 conv8(const u16* __restrict__ row, int t, int L, float w0, float w1, float w2, float bb) {
;   const uint4 u = *(const uint4*)(row + t);
;   const float um = (t > 0) ? bf2f(row[t - 1]) : 0.f;
;   const float up = (t + 8 < L) ? bf2f(row[t + 8]) : 0.f;
;   float x[10];
;   x[0] = um;
;   x[1] = bflo(u.x); x[2] = bfhi(u.x); x[3] = bflo(u.y); x[4] = bfhi(u.y);
;   x[5] = bflo(u.z); x[6] = bfhi(u.z); x[7] = bflo(u.w); x[8] = bfhi(u.w);
;   x[9] = up;
;   F8 o;
; #pragma unroll
;   for (int j = 0; j < 8; ++j) o.v[j] = x[j] * w0 + x[j + 1] * w1 + x[j + 2] * w2 + bb;
;   return o;
; }
; template <int BG>
; DEV void hyena_item_mfma(const Params& p, int g, int item, char* smem, int half) {
;     ...
;     for (int e0 = tid; e0 < BG * L / 8; e0 += 256 * 4) {
;       F8 x[4];
;       uint4 y[4];
; #pragma unroll
;       for (int u = 0; u < 4; ++u) {
;         const int e = e0 + 256 * u;
;         const int bl = e / (L / 8), t = (e % (L / 8)) * 8;
;         const int b = bgi * BG + bl;
;         x[u] = conv8(UHY + ((size_t)b * 1536 + c) * L, t, L, wx0_0, wx0_1, wx0_2, bx0);
;         y[u] = *(const uint4*)(Vl + ((t >> 6) * BG + bl) * VROW + (t & 63) * 2);
;       }
; #pragma unroll
;       for (int u = 0; u < 4; ++u) {
;         const int e = e0 + 256 * u;
;         const int bl = e / (L / 8), t = (e % (L / 8)) * 8;
;         const int b = bgi * BG + bl;
;         *(uint4*)(UHY + ((size_t)b * 1536 + 1024 + c) * L + t) =
;             make_uint4(pack2(bflo(y[u].x) * x[u].v[0], bfhi(y[u].x) * x[u].v[1]), pack2(bflo(y[u].y) * x[u].v[2], bfhi(y[u].y) * x[u].v[3]),
;                        pack2(bflo(y[u].z) * x[u].v[4], bfhi(y[u].z) * x[u].v[5]), pack2(bflo(y[u].w) * x[u].v[6], bfhi(y[u].w) * x[u].v[7]));
;       }
	v_lshlrev_b32_e32 v0, 16, v4
	v_and_b32_e32 v1, 0xffff0000, v4
	v_mul_f32_e32 v0, v53, v0
	v_mul_f32_e32 v1, v36, v1
	s_nop 0
	v_cvt_pk_bf16_f32 v0, v0, v1
	v_lshlrev_b32_e32 v1, 16, v5
	v_and_b32_e32 v2, 0xffff0000, v5
	v_mul_f32_e32 v1, v20, v1
	v_mul_f32_e32 v2, v58, v2
	s_nop 0
	v_cvt_pk_bf16_f32 v1, v1, v2
	v_lshlrev_b32_e32 v2, 16, v6
	v_and_b32_e32 v3, 0xffff0000, v6
	v_mul_f32_e32 v2, v21, v2
	v_mul_f32_e32 v3, v59, v3
	s_nop 0
	v_cvt_pk_bf16_f32 v2, v2, v3
	v_lshlrev_b32_e32 v3, 16, v7
	v_and_b32_e32 v4, 0xffff0000, v7
	v_mul_f32_e32 v3, v22, v3
	v_mul_f32_e32 v4, v23, v4
	s_nop 0
	v_cvt_pk_bf16_f32 v3, v3, v4
	v_lshl_add_u64 v[4:5], s[74:75], 0, v[16:17]
	v_mov_b32_e32 v33, v165
	v_lshl_add_u64 v[4:5], v[4:5], 0, v[32:33]
	v_add_f32_e32 v55, v41, v55
	global_store_dwordx4 v[4:5], v[0:3], off
	v_add_f32_e32 v71, v41, v12
	v_add_u32_e32 v12, s10, v45
	s_waitcnt lgkmcnt(0)
	v_lshlrev_b32_e32 v0, 16, v8
	v_and_b32_e32 v1, 0xffff0000, v8
	v_mul_f32_e32 v0, v55, v0
	v_mul_f32_e32 v1, v37, v1
	s_nop 0
	v_cvt_pk_bf16_f32 v0, v0, v1
	v_lshlrev_b32_e32 v1, 16, v9
	v_and_b32_e32 v2, 0xffff0000, v9
	v_mul_f32_e32 v1, v24, v1
	v_mul_f32_e32 v2, v56, v2
	s_nop 0
	v_cvt_pk_bf16_f32 v1, v1, v2
	v_lshlrev_b32_e32 v2, 16, v10
	v_and_b32_e32 v3, 0xffff0000, v10
	v_mad_u32_u24 v12, v12, s60, v42
	v_mul_f32_e32 v2, v25, v2
	v_mul_f32_e32 v3, v57, v3
	v_add_f32_e32 v27, v41, v27
	v_fmac_f32_e32 v35, v40, v13
	v_fmac_f32_e32 v62, v40, v14
	ds_read_b128 v[12:15], v12 offset:32896
	s_nop 0
	v_cvt_pk_bf16_f32 v2, v2, v3
	v_lshlrev_b32_e32 v3, 16, v11
	v_and_b32_e32 v4, 0xffff0000, v11
	v_mul_f32_e32 v3, v26, v3
	v_mul_f32_e32 v4, v27, v4
	v_add_u32_e32 v164, 0x400, v34
	s_nop 0
	v_cvt_pk_bf16_f32 v3, v3, v4
	v_lshl_add_u64 v[4:5], v[164:165], 0, s[18:19]
	v_lshlrev_b64 v[4:5], 13, v[4:5]
	v_lshl_add_u64 v[6:7], v[28:29], 0, v[4:5]
	v_add_f32_e32 v35, v41, v35
	v_add_f32_e32 v62, v41, v62
	global_store_dwordx4 v[6:7], v[0:3], off
	v_add_co_u32_e32 v43, vcc, 0x400, v43
	s_waitcnt lgkmcnt(0)
	v_lshlrev_b32_e32 v0, 16, v12
	v_and_b32_e32 v1, 0xffff0000, v12
	v_mul_f32_e32 v0, v35, v0
	v_mul_f32_e32 v1, v62, v1
	s_nop 0
	v_cvt_pk_bf16_f32 v0, v0, v1
	v_lshlrev_b32_e32 v1, 16, v13
	v_and_b32_e32 v2, 0xffff0000, v13
	v_mul_f32_e32 v1, v66, v1
	v_mul_f32_e32 v2, v67, v2
	s_nop 0
	v_cvt_pk_bf16_f32 v1, v1, v2
	v_lshlrev_b32_e32 v2, 16, v14
	v_and_b32_e32 v3, 0xffff0000, v14
	v_mul_f32_e32 v2, v68, v2
	v_mul_f32_e32 v3, v69, v3
	s_xor_b64 s[8:9], vcc, -1
	s_add_i32 s10, s10, 2
	s_nop 0
	v_cvt_pk_bf16_f32 v2, v2, v3
	v_lshlrev_b32_e32 v3, 16, v15
	s_and_b64 s[8:9], exec, s[8:9]
	v_mul_f32_e32 v3, v70, v3
	v_and_b32_e32 v6, 0xffff0000, v15
	v_lshl_add_u64 v[4:5], v[30:31], 0, v[4:5]
	v_add_u32_e32 v49, 0x2000, v49
	s_or_b64 s[4:5], s[8:9], s[4:5]
	v_add_u32_e32 v144, 0x4000, v144
	v_mul_f32_e32 v6, v71, v6
	s_nop 0
	v_cvt_pk_bf16_f32 v3, v3, v6
	global_store_dwordx4 v[4:5], v[0:3], off
	s_andn2_b64 exec, exec, s[4:5]
	s_cbranch_execz .LBB0_721
.LBB0_796:
	v_add_u32_e32 v0, s10, v50
	v_mul_u32_u24_e32 v164, 0x600, v0
	v_lshl_add_u64 v[0:1], v[164:165], 0, s[18:19]
	v_lshlrev_b64 v[4:5], 13, v[0:1]
	v_lshl_add_u64 v[0:1], v[28:29], 0, v[4:5]
	global_load_dwordx4 v[12:15], v[0:1], off
	v_mov_b32_e32 v53, 0
	v_mov_b32_e32 v51, 0
	v_mov_b32_e32 v76, 0
	s_and_saveexec_b64 s[8:9], s[0:1]
	global_load_ushort v76, v[0:1], off offset:-2
.LBB0_798:
	s_or_b64 exec, exec, s[8:9]
	v_and_b32_e32 v6, 0xff8, v49
	v_lshl_add_u64 v[4:5], s[74:75], 0, v[4:5]
	v_lshlrev_b32_e32 v32, 1, v6
	v_mov_b32_e32 v33, v165
	v_lshl_add_u64 v[4:5], v[4:5], 0, v[32:33]
	global_load_ushort v52, v[0:1], off offset:16
	global_load_dwordx4 v[20:23], v[4:5], off
	v_add_u32_e32 v0, s10, v47
	v_mul_u32_u24_e32 v0, 0x90, v0
	v_and_b32_e32 v1, 0x70, v144
	v_add3_u32 v0, s15, v0, v1
	ds_read_b128 v[0:3], v0 offset:32896
	v_cmp_ne_u32_e32 vcc, 0, v6
	v_mov_b32_e32 v77, 0
	s_and_saveexec_b64 s[8:9], vcc
	global_load_ushort v77, v[4:5], off offset:-2
.LBB0_800:
	s_or_b64 exec, exec, s[8:9]
	s_movk_i32 s8, 0xff8
	v_cmp_ne_u32_e32 vcc, s8, v6
	v_mov_b32_e32 v55, 0
	v_mov_b32_e32 v54, 0
	v_mov_b32_e32 v78, 0
	s_and_saveexec_b64 s[8:9], vcc
	global_load_ushort v78, v[4:5], off offset:16
.LBB0_802:
	s_or_b64 exec, exec, s[8:9]
	v_add_u32_e32 v8, s10, v46
	v_mul_u32_u24_e32 v34, 0x600, v8
	v_mov_b32_e32 v35, v165
	v_lshl_add_u64 v[8:9], v[34:35], 0, s[18:19]
	v_lshlrev_b64 v[10:11], 13, v[8:9]
	v_lshl_add_u64 v[8:9], v[28:29], 0, v[10:11]
	global_load_dwordx4 v[24:27], v[8:9], off
	v_add_u32_e32 v4, s10, v44
	v_mad_u32_u24 v4, v4, s60, v42
	ds_read_b128 v[4:7], v4 offset:32896
	v_mov_b32_e32 v79, 0
	s_and_saveexec_b64 s[8:9], s[0:1]
	global_load_ushort v79, v[8:9], off offset:-2
.LBB0_804:
	s_or_b64 exec, exec, s[8:9]
	v_lshl_add_u64 v[36:37], v[30:31], 0, v[10:11]
	global_load_ushort v56, v[8:9], off offset:16
	global_load_dwordx4 v[16:19], v[36:37], off
	global_load_ushort v35, v[36:37], off offset:-2
	v_add_u32_e32 v8, s10, v48
	v_mad_u32_u24 v8, v8, s60, v42
	ds_read_b128 v[8:11], v8 offset:32896
	v_mov_b32_e32 v33, 0
	v_mov_b32_e32 v80, 0
	s_and_saveexec_b64 s[8:9], s[36:37]
	global_load_ushort v80, v[36:37], off offset:16
	s_or_b64 exec, exec, s[8:9]
	s_branch .LBB0_795
